# v96 + counted wait at out-proj block 0: wait only for its own two residual loads (vmcnt 12), prefetches stay in flight
# speedup vs baseline: 1.0206x; 1.0206x over previous
.LBB0_1279:
	s_lshl_b32 s15, s54, 8
	s_add_i32 s15, s15, s79
	v_mbcnt_lo_u32_b32 v156, -1, 0
	v_mbcnt_hi_u32_b32 v156, -1, v156
	v_readlane_b32 s17, v252, 33
	v_and_or_b32 v140, v156, 15, s15
	s_lshl_b32 s15, s53, 8
	v_ashrrev_i32_e32 v141, 1, v156
	s_or_b32 s15, s15, s17
	v_and_b32_e32 v141, -8, v141
	v_add_u32_e32 v146, s15, v141
	v_ashrrev_i32_e32 v141, 31, v140
	v_ashrrev_i32_e32 v147, 31, v146
	v_lshlrev_b64 v[142:143], 11, v[140:141]
	v_lshl_add_u64 v[144:145], v[142:143], 0, v[146:147]
	v_lshlrev_b64 v[142:143], 2, v[144:145]
	v_lshl_add_u64 v[150:151], s[0:1], 0, v[142:143]
	global_load_dwordx4 v[158:161], v[150:151], off offset:16 nt
	global_load_dwordx4 v[162:165], v[150:151], off nt
	v_mov_b32_e32 v226, v150
	v_mov_b32_e32 v227, v151
	v_mov_b32_e32 v246, 0x20000
	v_mov_b32_e32 v247, 0
	v_lshl_add_u64 v[228:229], v[226:227], 0, v[246:247]
	global_load_dwordx4 v[168:171], v[228:229], off nt
	global_load_dwordx4 v[172:175], v[228:229], off offset:16 nt
	global_load_dwordx4 v[176:179], v[228:229], off offset:512 nt
	global_load_dwordx4 v[180:183], v[228:229], off offset:528 nt
	v_mov_b32_e32 v246, 0x40000
	v_mov_b32_e32 v247, 0
	v_lshl_add_u64 v[228:229], v[226:227], 0, v[246:247]
	global_load_dwordx4 v[184:187], v[228:229], off nt
	global_load_dwordx4 v[188:191], v[228:229], off offset:16 nt
	global_load_dwordx4 v[192:195], v[228:229], off offset:512 nt
	global_load_dwordx4 v[206:209], v[228:229], off offset:528 nt
	v_mov_b32_e32 v246, 0x60000
	v_mov_b32_e32 v247, 0
	v_lshl_add_u64 v[228:229], v[226:227], 0, v[246:247]
	global_load_dwordx4 v[210:213], v[228:229], off nt
	global_load_dwordx4 v[214:217], v[228:229], off offset:16 nt
	global_load_dwordx4 v[218:221], v[228:229], off offset:512 nt
	global_load_dwordx4 v[222:225], v[228:229], off offset:528 nt
	v_lshl_add_u64 v[152:153], s[10:11], 0, v[142:143]
	v_cndmask_b32_e64 v142, 0, 1, s[12:13]
	v_cmp_ne_u32_e64 s[92:93], 1, v142
	s_andn2_b64 vcc, exec, s[12:13]
	v_lshl_add_u64 v[142:143], v[146:147], 2, s[4:5]
	v_lshl_add_u64 v[148:149], v[144:145], 1, s[6:7]
	s_waitcnt vmcnt(12)
	v_pk_add_f32 v[124:125], v[124:125], v[160:161]
	v_pk_add_f32 v[128:129], v[128:129], v[164:165]
	v_pk_add_f32 v[126:127], v[126:127], v[162:163]
	v_pk_add_f32 v[122:123], v[122:123], v[158:159]
	global_store_dwordx4 v[152:153], v[126:129], off
	global_store_dwordx4 v[152:153], v[122:125], off offset:16
	s_cbranch_vccnz .LBB0_1281
	global_load_dwordx4 v[234:237], v[142:143], off offset:16
	global_load_dwordx4 v[230:233], v[142:143], off
	global_load_dwordx4 v[242:245], v[142:143], off offset:528
	global_load_dwordx4 v[238:241], v[142:143], off offset:512
	s_waitcnt vmcnt(0)
	v_mov_b32_e32 v158, v234
	v_mov_b32_e32 v159, v235
	v_mov_b32_e32 v160, v236
	v_mov_b32_e32 v161, v237
	v_mov_b32_e32 v162, v230
	v_mov_b32_e32 v163, v231
	v_mov_b32_e32 v164, v232
	v_mov_b32_e32 v165, v233
	v_pk_mul_f32 v[166:167], v[124:125], v[160:161]
	v_pk_mul_f32 v[162:163], v[126:127], v[162:163]
	v_pk_mul_f32 v[126:127], v[126:127], v[126:127]
	v_pk_mul_f32 v[164:165], v[128:129], v[164:165]
	v_pk_mul_f32 v[128:129], v[128:129], v[128:129]
	v_add_f32_e32 v126, v126, v127
	v_add_f32_e32 v126, v128, v126
	v_pk_mul_f32 v[160:161], v[122:123], v[158:159]
	v_pk_mul_f32 v[122:123], v[122:123], v[122:123]
	v_add_f32_e32 v126, v129, v126
	v_add_f32_e32 v122, v122, v126
	v_pk_mul_f32 v[124:125], v[124:125], v[124:125]
	v_add_f32_e32 v122, v123, v122
	v_add_f32_e32 v122, v124, v122
	v_add_f32_e32 v122, v125, v122
	v_cvt_pk_bf16_f32 v158, v162, v163
	v_cvt_pk_bf16_f32 v159, v164, v165
	v_cvt_pk_bf16_f32 v160, v160, v161
	v_cvt_pk_bf16_f32 v161, v166, v167
	global_store_dwordx4 v[148:149], v[158:161], off
	s_branch .LBB0_1282
